# thin phases: nt also on the residual-stream (H) stores
# baseline (speedup 1.0000x reference)
.LBB0_666:
	v_pk_mul_f32 v[88:89], v[30:31], v[30:31]
	v_pk_mul_f32 v[90:91], v[26:27], v[26:27]
	v_pk_mul_f32 v[84:85], v[32:33], v[32:33]
	v_pk_mul_f32 v[86:87], v[28:29], v[28:29]
	v_mov_b32_e32 v92, v88
	v_mov_b32_e32 v93, v90
	v_mov_b32_e32 v90, v89
	v_pk_mul_f32 v[80:81], v[24:25], v[24:25]
	v_pk_mul_f32 v[82:83], v[22:23], v[22:23]
	v_pk_add_f32 v[88:89], v[92:93], v[90:91]
	v_mov_b32_e32 v90, v84
	v_mov_b32_e32 v91, v86
	v_mov_b32_e32 v86, v85
	v_pk_add_f32 v[84:85], v[90:91], v[86:87]
	v_pk_mov_b32 v[86:87], v[82:83], v[80:81] op_sel:[1,0]
	v_mov_b32_e32 v83, v81
	v_pk_add_f32 v[80:81], v[86:87], v[82:83]
	v_pk_add_f32 v[84:85], v[88:89], v[84:85]
	v_pk_add_f32 v[80:81], v[80:81], v[80:81] op_sel_hi:[0,1]
	v_mul_f32_e32 v80, v18, v18
	v_pk_fma_f32 v[82:83], v[18:19], v[18:19], v[80:81] op_sel_hi:[1,1,0]
	v_mul_f32_e32 v80, v20, v20
	v_pk_add_f32 v[84:85], v[84:85], v[84:85] op_sel_hi:[0,1]
	v_pk_fma_f32 v[86:87], v[20:21], v[20:21], v[80:81] op_sel_hi:[1,1,0]
	v_mul_f32_e32 v82, v14, v14
	v_mul_f32_e32 v86, v15, v15
	v_mul_f32_e32 v80, v16, v16
	v_mul_f32_e32 v84, v17, v17
	v_pk_mul_f32 v[76:77], v[12:13], v[12:13]
	v_pk_mul_f32 v[78:79], v[10:11], v[10:11]
	v_pk_add_f32 v[82:83], v[82:83], v[86:87]
	v_pk_add_f32 v[80:81], v[80:81], v[84:85]
	s_waitcnt vmcnt(2)
	v_lshlrev_b32_e32 v86, 16, v48
	v_pk_add_f32 v[80:81], v[82:83], v[80:81]
	v_pk_mov_b32 v[82:83], v[78:79], v[76:77] op_sel:[1,0]
	v_mov_b32_e32 v79, v77
	v_pk_add_f32 v[76:77], v[82:83], v[78:79]
	v_pk_add_f32 v[80:81], v[80:81], v[80:81] op_sel_hi:[0,1]
	v_pk_add_f32 v[76:77], v[76:77], v[76:77] op_sel_hi:[0,1]
	v_mul_f32_e32 v76, v6, v6
	v_pk_fma_f32 v[78:79], v[6:7], v[6:7], v[76:77] op_sel_hi:[1,1,0]
	v_mul_f32_e32 v76, v8, v8
	v_pk_fma_f32 v[82:83], v[8:9], v[8:9], v[76:77] op_sel_hi:[1,1,0]
	v_mul_f32_e32 v78, v2, v2
	v_mul_f32_e32 v82, v3, v3
	v_mul_f32_e32 v76, v4, v4
	v_mul_f32_e32 v80, v5, v5
	v_pk_add_f32 v[78:79], v[78:79], v[82:83]
	v_pk_add_f32 v[76:77], v[76:77], v[80:81]
	v_and_b32_e32 v83, 0xffff0000, v50
	v_pk_add_f32 v[76:77], v[78:79], v[76:77]
	v_and_b32_e32 v87, 0xffff0000, v48
	v_add_f32_e32 v78, v76, v77
	ds_bpermute_b32 v79, v1, v78
	s_waitcnt vmcnt(1)
	v_lshlrev_b32_e32 v90, 16, v46
	v_and_b32_e32 v91, 0xffff0000, v46
	s_mul_i32 s1, s4, 0x6000
	s_and_b64 s[4:5], exec, s[6:7]
	s_waitcnt lgkmcnt(0)
	v_add_f32_e32 v81, v78, v79
	ds_bpermute_b32 v82, v62, v81
	v_lshlrev_b32_e32 v78, 16, v52
	v_and_b32_e32 v79, 0xffff0000, v52
	s_waitcnt vmcnt(0)
	v_lshlrev_b32_e32 v94, 16, v44
	v_and_b32_e32 v95, 0xffff0000, v44
	s_waitcnt lgkmcnt(0)
	v_add_f32_e32 v52, v81, v82
	ds_bpermute_b32 v85, v63, v52
	v_lshlrev_b32_e32 v82, 16, v50
	s_cselect_b32 s1, 0x18000, s1
	v_add_u32_e32 v99, s1, v67
	v_lshlrev_b32_e32 v88, 16, v49
	s_waitcnt lgkmcnt(0)
	v_add_f32_e32 v50, v52, v85
	ds_bpermute_b32 v52, v64, v50
	v_and_b32_e32 v89, 0xffff0000, v49
	v_lshlrev_b32_e32 v92, 16, v47
	v_and_b32_e32 v93, 0xffff0000, v47
	v_lshlrev_b32_e32 v80, 16, v53
	s_waitcnt lgkmcnt(0)
	v_add_f32_e32 v48, v50, v52
	ds_bpermute_b32 v50, v65, v48
	v_and_b32_e32 v81, 0xffff0000, v53
	v_lshlrev_b32_e32 v84, 16, v51
	v_and_b32_e32 v85, 0xffff0000, v51
	v_lshlrev_b32_e32 v60, 16, v58
	s_waitcnt lgkmcnt(0)
	v_add_f32_e32 v46, v48, v50
	ds_bpermute_b32 v48, v66, v46
	ds_read_b128 v[50:53], v99 offset:1024
	v_and_b32_e32 v61, 0xffff0000, v58
	v_lshlrev_b32_e32 v58, 16, v59
	v_and_b32_e32 v59, 0xffff0000, v59
	s_waitcnt lgkmcnt(1)
	v_add_f32_e32 v44, v46, v48
	v_fmamk_f32 v44, v44, 0x3a000000, v73
	v_rsq_f32_e32 v98, v44
	ds_read_b128 v[46:49], v99
	v_lshlrev_b32_e32 v96, 16, v45
	v_and_b32_e32 v97, 0xffff0000, v45
	v_pk_mul_f32 v[44:45], v[30:31], v[98:99] op_sel_hi:[1,0]
	v_pk_mul_f32 v[30:31], v[32:33], v[98:99] op_sel_hi:[1,0]
	v_lshlrev_b32_e32 v74, 16, v56
	v_and_b32_e32 v75, 0xffff0000, v56
	s_waitcnt lgkmcnt(0)
	v_pk_fma_f32 v[30:31], v[48:49], v[30:31], v[58:59]
	v_pk_fma_f32 v[32:33], v[46:47], v[44:45], v[60:61]
	v_pk_mul_f32 v[48:49], v[26:27], v[98:99] op_sel_hi:[1,0]
	ds_read_b128 v[44:47], v99 offset:2048
	v_pk_mul_f32 v[26:27], v[28:29], v[98:99] op_sel_hi:[1,0]
	v_pk_fma_f32 v[28:29], v[50:51], v[48:49], v[74:75]
	ds_read_b128 v[48:51], v99 offset:3072
	v_lshlrev_b32_e32 v56, 16, v57
	v_and_b32_e32 v57, 0xffff0000, v57
	v_lshlrev_b32_e32 v76, 16, v54
	v_and_b32_e32 v77, 0xffff0000, v54
	v_lshlrev_b32_e32 v54, 16, v55
	v_and_b32_e32 v55, 0xffff0000, v55
	v_pk_fma_f32 v[26:27], v[52:53], v[26:27], v[56:57]
	v_pk_mul_f32 v[52:53], v[22:23], v[98:99] op_sel_hi:[1,0]
	v_pk_mul_f32 v[22:23], v[24:25], v[98:99] op_sel_hi:[1,0]
	s_waitcnt lgkmcnt(1)
	v_pk_fma_f32 v[24:25], v[44:45], v[52:53], v[76:77]
	v_pk_fma_f32 v[22:23], v[46:47], v[22:23], v[54:55]
	v_pk_mul_f32 v[52:53], v[18:19], v[98:99] op_sel_hi:[1,0]
	v_pk_mul_f32 v[18:19], v[20:21], v[98:99] op_sel_hi:[1,0]
	ds_read_b128 v[44:47], v99 offset:4096
	s_waitcnt lgkmcnt(1)
	v_pk_fma_f32 v[18:19], v[50:51], v[18:19], v[80:81]
	v_pk_fma_f32 v[20:21], v[48:49], v[52:53], v[78:79]
	ds_read_b128 v[48:51], v99 offset:5120
	v_pk_mul_f32 v[52:53], v[14:15], v[98:99] op_sel_hi:[1,0]
	v_pk_mul_f32 v[14:15], v[16:17], v[98:99] op_sel_hi:[1,0]
	s_waitcnt lgkmcnt(1)
	v_pk_fma_f32 v[16:17], v[44:45], v[52:53], v[82:83]
	v_pk_fma_f32 v[14:15], v[46:47], v[14:15], v[84:85]
	v_pk_mul_f32 v[52:53], v[10:11], v[98:99] op_sel_hi:[1,0]
	v_pk_mul_f32 v[10:11], v[12:13], v[98:99] op_sel_hi:[1,0]
	ds_read_b128 v[44:47], v99 offset:6144
	s_waitcnt lgkmcnt(1)
	v_pk_fma_f32 v[10:11], v[50:51], v[10:11], v[88:89]
	v_pk_fma_f32 v[12:13], v[48:49], v[52:53], v[86:87]
	ds_read_b128 v[48:51], v99 offset:7168
	v_pk_mul_f32 v[52:53], v[6:7], v[98:99] op_sel_hi:[1,0]
	v_pk_mul_f32 v[6:7], v[8:9], v[98:99] op_sel_hi:[1,0]
	s_waitcnt lgkmcnt(1)
	v_pk_fma_f32 v[8:9], v[44:45], v[52:53], v[90:91]
	v_pk_fma_f32 v[6:7], v[46:47], v[6:7], v[92:93]
	v_pk_mul_f32 v[44:45], v[2:3], v[98:99] op_sel_hi:[1,0]
	v_mov_b32_e32 v46, v33
	v_mov_b32_e32 v47, v29
	v_pk_mul_f32 v[2:3], v[4:5], v[98:99] op_sel_hi:[1,0]
	s_waitcnt lgkmcnt(0)
	v_pk_fma_f32 v[4:5], v[48:49], v[44:45], v[94:95]
	v_mov_b32_e32 v44, v32
	v_mov_b32_e32 v45, v28
	v_pk_mul_f32 v[46:47], v[46:47], v[46:47]
	v_mov_b32_e32 v48, v31
	v_mov_b32_e32 v49, v27
	v_pk_fma_f32 v[44:45], v[44:45], v[44:45], v[46:47]
	v_mov_b32_e32 v46, v30
	v_mov_b32_e32 v47, v26
	v_pk_mul_f32 v[48:49], v[48:49], v[48:49]
	v_pk_fma_f32 v[2:3], v[50:51], v[2:3], v[96:97]
	v_pk_fma_f32 v[46:47], v[46:47], v[46:47], v[48:49]
	v_pk_mul_f32 v[48:49], v[24:25], v[24:25]
	v_pk_add_f32 v[44:45], v[44:45], v[46:47]
	v_pk_mul_f32 v[46:47], v[22:23], v[22:23]
	v_pk_add_f32 v[44:45], v[44:45], v[44:45] op_sel_hi:[0,1]
	v_pk_mov_b32 v[50:51], v[48:49], v[46:47] op_sel:[1,0]
	v_mov_b32_e32 v49, v47
	v_mul_f32_e32 v44, v20, v20
	v_pk_add_f32 v[46:47], v[50:51], v[48:49]
	v_pk_fma_f32 v[48:49], v[20:21], v[20:21], v[44:45] op_sel_hi:[1,1,0]
	v_mul_f32_e32 v44, v18, v18
	v_pk_add_f32 v[46:47], v[46:47], v[46:47] op_sel_hi:[0,1]
	v_pk_fma_f32 v[50:51], v[18:19], v[18:19], v[44:45] op_sel_hi:[1,1,0]
	v_mul_f32_e32 v48, v16, v16
	v_mul_f32_e32 v50, v17, v17
	v_mul_f32_e32 v46, v14, v14
	v_mul_f32_e32 v44, v15, v15
	v_pk_add_f32 v[48:49], v[48:49], v[50:51]
	v_pk_add_f32 v[44:45], v[46:47], v[44:45]
	v_pk_mul_f32 v[46:47], v[10:11], v[10:11]
	v_pk_add_f32 v[44:45], v[48:49], v[44:45]
	v_pk_mul_f32 v[48:49], v[12:13], v[12:13]
	v_pk_add_f32 v[44:45], v[44:45], v[44:45] op_sel_hi:[0,1]
	v_pk_mov_b32 v[50:51], v[48:49], v[46:47] op_sel:[1,0]
	v_mov_b32_e32 v49, v47
	v_mul_f32_e32 v44, v8, v8
	v_pk_add_f32 v[46:47], v[50:51], v[48:49]
	v_pk_fma_f32 v[48:49], v[8:9], v[8:9], v[44:45] op_sel_hi:[1,1,0]
	v_mul_f32_e32 v44, v6, v6
	v_pk_add_f32 v[46:47], v[46:47], v[46:47] op_sel_hi:[0,1]
	v_pk_fma_f32 v[50:51], v[6:7], v[6:7], v[44:45] op_sel_hi:[1,1,0]
	v_mul_f32_e32 v48, v4, v4
	v_mul_f32_e32 v50, v5, v5
	v_mul_f32_e32 v46, v2, v2
	v_mul_f32_e32 v44, v3, v3
	v_pk_add_f32 v[48:49], v[48:49], v[50:51]
	v_pk_add_f32 v[44:45], v[46:47], v[44:45]
	s_add_i32 s0, s0, s12
	v_pk_add_f32 v[44:45], v[48:49], v[44:45]
	s_cmpk_lt_i32 s0, 0x4400
	v_add_f32_e32 v46, v44, v45
	ds_bpermute_b32 v47, v1, v46
	v_cvt_pk_bf16_f32 v44, v32, v33
	v_cvt_pk_bf16_f32 v45, v30, v31
	global_store_dwordx2 v[42:43], v[44:45], off nt
	v_cvt_pk_bf16_f32 v44, v28, v29
	s_waitcnt lgkmcnt(0)
	v_add_f32_e32 v46, v46, v47
	ds_bpermute_b32 v47, v62, v46
	v_cvt_pk_bf16_f32 v45, v26, v27
	global_store_dwordx2 v[42:43], v[44:45], off offset:512 nt
	v_cvt_pk_bf16_f32 v44, v24, v25
	v_cvt_pk_bf16_f32 v45, v22, v23
	s_waitcnt lgkmcnt(0)
	v_add_f32_e32 v46, v46, v47
	ds_bpermute_b32 v47, v63, v46
	global_store_dwordx2 v[42:43], v[44:45], off offset:1024 nt
	v_cvt_pk_bf16_f32 v44, v20, v21
	v_cvt_pk_bf16_f32 v45, v18, v19
	global_store_dwordx2 v[42:43], v[44:45], off offset:1536 nt
	s_waitcnt lgkmcnt(0)
	v_add_f32_e32 v46, v46, v47
	ds_bpermute_b32 v47, v64, v46
	v_cvt_pk_bf16_f32 v44, v16, v17
	v_cvt_pk_bf16_f32 v45, v14, v15
	global_store_dwordx2 v[42:43], v[44:45], off offset:2048 nt
	v_cvt_pk_bf16_f32 v44, v12, v13
	s_waitcnt lgkmcnt(0)
	v_add_f32_e32 v46, v46, v47
	ds_bpermute_b32 v47, v65, v46
	v_cvt_pk_bf16_f32 v45, v10, v11
	global_store_dwordx2 v[42:43], v[44:45], off offset:2560 nt
	v_cvt_pk_bf16_f32 v44, v8, v9
	v_cvt_pk_bf16_f32 v45, v6, v7
	s_waitcnt lgkmcnt(0)
	v_add_f32_e32 v46, v46, v47
	ds_bpermute_b32 v47, v66, v46
	global_store_dwordx2 v[42:43], v[44:45], off offset:3072 nt
	v_cvt_pk_bf16_f32 v52, v4, v5
	v_cvt_pk_bf16_f32 v53, v2, v3
	s_waitcnt lgkmcnt(0)
	v_add_f32_e32 v44, v46, v47
	v_fmamk_f32 v44, v44, 0x3a000000, v73
	v_rsq_f32_e32 v54, v44
	ds_read_b128 v[44:47], v99 offset:8192
	ds_read_b128 v[48:51], v99 offset:16384
	global_store_dwordx2 v[42:43], v[52:53], off offset:3584 nt
	v_pk_mul_f32 v[32:33], v[32:33], v[54:55] op_sel_hi:[1,0]
	v_pk_mul_f32 v[30:31], v[30:31], v[54:55] op_sel_hi:[1,0]
	s_waitcnt lgkmcnt(0)
	v_pk_fma_f32 v[32:33], v[44:45], v[32:33], v[48:49]
	v_pk_fma_f32 v[30:31], v[46:47], v[30:31], v[50:51]
	v_cvt_pk_bf16_f32 v46, v32, v33
	v_pk_mul_f32 v[28:29], v[28:29], v[54:55] op_sel_hi:[1,0]
	v_cvt_pk_bf16_f32 v47, v30, v31
	ds_read_b128 v[30:33], v99 offset:9216
	ds_read_b128 v[42:45], v99 offset:17408
	v_pk_mul_f32 v[26:27], v[26:27], v[54:55] op_sel_hi:[1,0]
	v_lshl_add_u64 v[48:49], s[2:3], 1, v[38:39]
	global_store_dwordx2 v[48:49], v[46:47], off
	v_pk_mul_f32 v[24:25], v[24:25], v[54:55] op_sel_hi:[1,0]
	s_waitcnt lgkmcnt(0)
	v_pk_fma_f32 v[26:27], v[32:33], v[26:27], v[44:45]
	v_pk_fma_f32 v[28:29], v[30:31], v[28:29], v[42:43]
	v_pk_mul_f32 v[22:23], v[22:23], v[54:55] op_sel_hi:[1,0]
	v_cvt_pk_bf16_f32 v42, v28, v29
	v_cvt_pk_bf16_f32 v43, v26, v27
	ds_read_b128 v[26:29], v99 offset:10240
	ds_read_b128 v[30:33], v99 offset:18432
	global_store_dwordx2 v[48:49], v[42:43], off offset:512
	v_pk_mul_f32 v[20:21], v[20:21], v[54:55] op_sel_hi:[1,0]
	v_pk_mul_f32 v[18:19], v[18:19], v[54:55] op_sel_hi:[1,0]
	v_pk_mul_f32 v[16:17], v[16:17], v[54:55] op_sel_hi:[1,0]
	s_waitcnt lgkmcnt(0)
	v_pk_fma_f32 v[22:23], v[22:23], v[28:29], v[32:33]
	v_pk_fma_f32 v[24:25], v[24:25], v[26:27], v[30:31]
	v_pk_mul_f32 v[14:15], v[14:15], v[54:55] op_sel_hi:[1,0]
	v_cvt_pk_bf16_f32 v30, v24, v25
	v_cvt_pk_bf16_f32 v31, v22, v23
	ds_read_b128 v[22:25], v99 offset:11264
	ds_read_b128 v[26:29], v99 offset:19456
	global_store_dwordx2 v[48:49], v[30:31], off offset:1024
	v_pk_mul_f32 v[12:13], v[12:13], v[54:55] op_sel_hi:[1,0]
	v_pk_mul_f32 v[10:11], v[10:11], v[54:55] op_sel_hi:[1,0]
	v_pk_mul_f32 v[8:9], v[8:9], v[54:55] op_sel_hi:[1,0]
	s_waitcnt lgkmcnt(0)
	v_pk_fma_f32 v[18:19], v[18:19], v[24:25], v[28:29]
	v_pk_fma_f32 v[20:21], v[20:21], v[22:23], v[26:27]
	v_pk_mul_f32 v[6:7], v[6:7], v[54:55] op_sel_hi:[1,0]
	v_cvt_pk_bf16_f32 v26, v20, v21
	v_cvt_pk_bf16_f32 v27, v18, v19
	ds_read_b128 v[18:21], v99 offset:12288
	ds_read_b128 v[22:25], v99 offset:20480
	global_store_dwordx2 v[48:49], v[26:27], off offset:1536
	v_pk_mul_f32 v[4:5], v[4:5], v[54:55] op_sel_hi:[1,0]
	v_pk_mul_f32 v[2:3], v[2:3], v[54:55] op_sel_hi:[1,0]
	s_waitcnt lgkmcnt(0)
	v_pk_fma_f32 v[14:15], v[14:15], v[20:21], v[24:25]
	v_pk_fma_f32 v[16:17], v[16:17], v[18:19], v[22:23]
	s_nop 0
	v_cvt_pk_bf16_f32 v22, v16, v17
	v_cvt_pk_bf16_f32 v23, v14, v15
	ds_read_b128 v[14:17], v99 offset:13312
	ds_read_b128 v[18:21], v99 offset:21504
	global_store_dwordx2 v[48:49], v[22:23], off offset:2048
	s_waitcnt lgkmcnt(0)
	v_pk_fma_f32 v[10:11], v[10:11], v[16:17], v[20:21]
	v_pk_fma_f32 v[12:13], v[12:13], v[14:15], v[18:19]
	s_nop 0
	v_cvt_pk_bf16_f32 v18, v12, v13
	v_cvt_pk_bf16_f32 v19, v10, v11
	ds_read_b128 v[10:13], v99 offset:14336
	ds_read_b128 v[14:17], v99 offset:22528
	global_store_dwordx2 v[48:49], v[18:19], off offset:2560
	s_waitcnt lgkmcnt(0)
	v_pk_fma_f32 v[6:7], v[6:7], v[12:13], v[16:17]
	v_pk_fma_f32 v[8:9], v[8:9], v[10:11], v[14:15]
	s_nop 0
	v_cvt_pk_bf16_f32 v14, v8, v9
	v_cvt_pk_bf16_f32 v15, v6, v7
	ds_read_b128 v[6:9], v99 offset:15360
	ds_read_b128 v[10:13], v99 offset:23552
	global_store_dwordx2 v[48:49], v[14:15], off offset:3072
	s_waitcnt lgkmcnt(0)
	v_pk_fma_f32 v[4:5], v[4:5], v[6:7], v[10:11]
	v_pk_fma_f32 v[2:3], v[2:3], v[8:9], v[12:13]
	v_cvt_pk_bf16_f32 v4, v4, v5
	s_nop 0
	v_cvt_pk_bf16_f32 v5, v2, v3
	global_store_dwordx2 v[48:49], v[4:5], off offset:3584
	s_cbranch_scc0 .LBB0_672
